# diff attention: the two tile-constant T5 biases are read from LDS once per unit into registers instead of an LDS read + full wait per key tile; with the K-fragment prefetch behind the per-step barrier
# baseline (speedup 1.0000x reference)
; #define LAS __attribute__((address_space(3)))
;     int tid = threadIdx.x; asm volatile("" : "+v"(tid));
;     const int lane = tid & 63, wid = __builtin_amdgcn_readfirstlane(tid >> 6), r32 = lane & 31, hi = lane >> 5;
;     const int qg = wid >> 1, cmap = wid & 1;
;     const LAS float* tab = (const LAS float*)(lds + LDS_TAB) + hd * 257;
;     const int q0w = qblk * 128 + qg * 32;
;     bf16_t* Qrow = QO + (size_t)(R0 + q0w + r32) * 512 + hd * 128;
;     bf16x8 qf[4];
; #pragma unroll
;     for (int s = 0; s < 4; ++s) qf[s] = *(const bf16x8*)(Qrow + cmap * 64 + s * 16 + hi * 8);
;     const bf16_t* kbase = Kg + (size_t)R0 * 512 + hd * 128;
;     const bf16_t* vbase = Vg + (size_t)R0 * 512 + hd * 128;
;     const size_t g0 = dma_goff(wid, lane, 512), g1 = dma_goff(wid + 8, lane, 512);
;     const unsigned d0 = wid * 1024u, d1 = (wid + 8) * 1024u;
;     const unsigned kb0 = kbase_of(lane), kb1 = kb0 ^ 32u, vb0 = vbase_of(lane), vb1 = vb0 ^ 32u;
;     const int nt = S / 64;
;     ...
;     DIFF_DMA2(0, 0);
;     float mrun = 0.f, lrun = 0.f;
;     f32x16 O[4]; bf16x8 P[4];
; #pragma unroll
;     for (int e = 0; e < 4; ++e) { O[e] = (f32x16){}; P[e] = (bf16x8){}; }
;     const int qidx = q0w + r32;
;     const int ibq = 128 + 4 * hi - qidx;
;     const int ns = nt >> 1;
;     __syncthreads();
;     if (wid < 4) __builtin_amdgcn_s_setprio(1);
.LBB0_198:
	v_lshlrev_b32_e32 v10, 6, v171
	v_lshlrev_b32_e32 v9, 8, v171
	v_and_b32_e32 v10, 0x1c0, v10
	s_movk_i32 s9, 0x1800
	v_lshrrev_b32_e32 v11, 3, v3
	v_bfe_u32 v8, v3, 2, 4
	v_and_or_b32 v9, v9, s9, v10
	v_and_b32_e32 v10, 0xc0, v6
	v_and_b32_e32 v11, 2, v11
	v_bfe_u32 v3, v3, 1, 1
	v_lshlrev_b32_e32 v170, 2, v2
	v_lshlrev_b32_e32 v169, 3, v2
	v_bitop3_b32 v8, v8, v2, 3 bitop3:0x6c
	v_lshl_or_b32 v10, v2, 8, v10
	v_bitop3_b32 v3, v11, v2, v3 bitop3:0x36
	v_add_u32_e32 v2, s30, v0
	v_sub_u32_e32 v0, v170, v0
	v_lshl_or_b32 v3, v3, 4, v10
	v_lshlrev_b32_e32 v10, 3, v171
	v_subrev_u32_e32 v0, s29, v0
	v_and_b32_e32 v10, 8, v10
	v_subrev_u32_e32 v177, s5, v0
	v_add_u32_e32 v0, s35, v4
	v_or_b32_e32 v173, v3, v10
	v_bitop3_b32 v174, v3, 32, v10 bitop3:0x36
	v_sub_u32_e32 v176, v170, v2
	v_lshlrev_b64 v[2:3], 10, v[0:1]
	v_add_u32_e32 v0, s34, v6
	v_lshrrev_b32_e32 v0, 3, v0
	v_lshl_add_u64 v[2:3], s[10:11], 0, v[2:3]
	v_lshlrev_b32_e32 v6, 4, v7
	v_and_b32_e32 v7, 0xc0, v0
	v_or3_b32 v2, v7, v6, v2
	v_add_u32_e32 v0, s31, v4
	v_lshl_add_u64 v[164:165], s[22:23], 0, v[2:3]
	v_lshlrev_b64 v[2:3], 10, v[0:1]
	v_lshl_add_u64 v[2:3], s[10:11], 0, v[2:3]
	v_lshlrev_b32_e32 v0, 4, v5
	s_mul_i32 s8, s4, 0x404
	v_lshlrev_b32_e32 v8, 4, v8
	v_or3_b32 v2, v0, v7, v2
	v_mov_b32_e32 v14, v1
	v_mov_b32_e32 v15, v1
	v_or_b32_e32 v172, v8, v9
	s_add_i32 s25, s8, 0
	v_bitop3_b32 v175, v8, 32, v9 bitop3:0x36
	s_mov_b32 s5, s85
	v_lshl_add_u64 v[166:167], s[22:23], 0, v[2:3]
	v_mov_b32_e32 v0, v1
	v_mov_b32_e32 v2, v1
	v_mov_b32_e32 v3, v1
	v_mov_b32_e32 v4, v1
	v_mov_b32_e32 v5, v1
	v_mov_b32_e32 v6, v1
	v_mov_b32_e32 v7, v1
	v_mov_b32_e32 v8, v1
	v_mov_b32_e32 v9, v1
	v_mov_b32_e32 v10, v1
	v_mov_b32_e32 v11, v1
	v_mov_b32_e32 v12, v1
	v_mov_b32_e32 v13, v1
	v_mov_b64_e32 v[30:31], v[14:15]
	v_mov_b64_e32 v[46:47], v[14:15]
	v_mov_b64_e32 v[62:63], v[14:15]
	v_mov_b64_e32 v[78:79], v[14:15]
	s_add_i32 s25, s25, 0x20000
	s_add_i32 s26, s30, 0x7a
	s_lshl_b32 s27, s18, 10
	s_add_i32 s28, s30, 58
	s_mov_b32 s29, 0
	s_sub_i32 s30, 0, s30
	s_lshl_b64 s[8:9], s[4:5], 8
	s_lshl_b32 s31, s17, 7
	v_mov_b32_e32 v178, 0
	s_mov_b32 s34, 0x10000
	s_mov_b32 s35, 1
	v_mov_b64_e32 v[28:29], v[12:13]
	v_mov_b64_e32 v[26:27], v[10:11]
	v_mov_b64_e32 v[24:25], v[8:9]
	v_mov_b64_e32 v[22:23], v[6:7]
	v_mov_b64_e32 v[20:21], v[4:5]
	v_mov_b64_e32 v[18:19], v[2:3]
	v_mov_b64_e32 v[16:17], v[0:1]
	v_mov_b64_e32 v[44:45], v[12:13]
	v_mov_b64_e32 v[42:43], v[10:11]
	v_mov_b64_e32 v[40:41], v[8:9]
	v_mov_b64_e32 v[38:39], v[6:7]
	v_mov_b64_e32 v[36:37], v[4:5]
	v_mov_b64_e32 v[34:35], v[2:3]
	v_mov_b64_e32 v[32:33], v[0:1]
	v_mov_b64_e32 v[60:61], v[12:13]
	v_mov_b64_e32 v[58:59], v[10:11]
	v_mov_b64_e32 v[56:57], v[8:9]
	v_mov_b64_e32 v[54:55], v[6:7]
	v_mov_b64_e32 v[52:53], v[4:5]
	v_mov_b64_e32 v[50:51], v[2:3]
	v_mov_b64_e32 v[48:49], v[0:1]
	v_mov_b64_e32 v[76:77], v[12:13]
	v_mov_b64_e32 v[74:75], v[10:11]
	v_mov_b64_e32 v[72:73], v[8:9]
	v_mov_b64_e32 v[70:71], v[6:7]
	v_mov_b64_e32 v[68:69], v[4:5]
	v_mov_b64_e32 v[66:67], v[2:3]
	v_mov_b64_e32 v[64:65], v[0:1]
	v_mov_b32_e32 v15, 0
	v_readfirstlane_b32 s10, v166
	v_readfirstlane_b32 s11, v167
	s_nop 1
	v_subrev_u32_e32 v250, s10, v166
	v_subrev_u32_e32 v251, s10, v164
	v_add_u32_e32 v250, 0x1000, v250
	v_add_u32_e32 v251, 0x1000, v251
	s_add_u32 s10, s10, s8
	s_addc_u32 s11, s11, s9
	s_sub_u32 s10, s10, 0x21000
	s_subb_u32 s11, s11, 0
	v_writelane_b32 v247, s10, 0
	v_writelane_b32 v247, s11, 1
	v_mov_b32_e32 v254, s25
	ds_read_b32 v255, v254 offset:1024
	ds_read_b32 v254, v254

;     ...
;         { const int kq = st * 128;
;           const bool farR = (kq - q0w - 31 >= 91), farL = (kq + 63 - q0w <= -91), nr = !(farR || farL);
;           diff_step<true, false>(KA, VA, tab, qf, O, P, mrun, lrun, nr ? 0.f : (farR ? tab[256] : tab[0]), kq + ibq, kb0, kb1, vb0, vb1, nr, st == 0); }
.LBB0_202:
	s_cmp_ge_i32 s29, s26
	s_cselect_b64 s[10:11], -1, 0
	s_cmp_lt_i32 s29, s26
	s_cselect_b64 s[4:5], -1, 0
	s_add_i32 s37, s30, s29
	s_cmpk_gt_i32 s37, 0xff66
	s_cselect_b64 s[56:57], -1, 0
	s_and_b64 s[4:5], s[4:5], s[56:57]
	s_and_b64 vcc, exec, s[4:5]
	v_mov_b32_e32 v0, 0
	s_cbranch_vccnz .LBB0_207
	s_andn2_b64 vcc, exec, s[10:11]
	s_cbranch_vccnz .LBB0_205
	v_mov_b32_e32 v0, v255
	s_cbranch_execz .LBB0_206
	s_branch .LBB0_207
.LBB0_205:
.LBB0_206:
	s_waitcnt lgkmcnt(0)
	v_mov_b32_e32 v0, v254

;     ...
;         { const int kq = st * 128 + 64;
;           const bool farR = (kq - q0w - 31 >= 91), farL = (kq + 63 - q0w <= -91), nr = !(farR || farL);
;           diff_step<true, true>(KB, VA, tab, qf, O, P, mrun, lrun, nr ? 0.f : (farR ? tab[256] : tab[0]), kq + ibq, kb0, kb1, vb0, vb1, nr); }
.LBB0_214:
	s_cmp_ge_i32 s29, s28
	s_cselect_b64 s[10:11], -1, 0
	s_cmp_lt_i32 s29, s28
	s_cselect_b64 s[4:5], -1, 0
	s_cmpk_gt_i32 s37, 0xff26
	s_cselect_b64 s[56:57], -1, 0
	s_and_b64 s[4:5], s[4:5], s[56:57]
	s_and_b64 vcc, exec, s[4:5]
	v_mov_b32_e32 v4, 0
	s_cbranch_vccnz .LBB0_220
	s_andn2_b64 vcc, exec, s[10:11]
	s_cbranch_vccnz .LBB0_218
	v_mov_b32_e32 v4, v255
	s_cbranch_execz .LBB0_219
	s_branch .LBB0_220

;     ...
;         { const int kq = st * 128 + 64;
;           const bool farR = (kq - q0w - 31 >= 91), farL = (kq + 63 - q0w <= -91), nr = !(farR || farL);
;           diff_step<true, true>(KB, VA, tab, qf, O, P, mrun, lrun, nr ? 0.f : (farR ? tab[256] : tab[0]), kq + ibq, kb0, kb1, vb0, vb1, nr); }
.LBB0_218:
.LBB0_219:
	s_waitcnt lgkmcnt(0)
	v_mov_b32_e32 v4, v254
